# speedup vs baseline: 1.0239x; 1.0239x over previous
;     __device__ __forceinline__ bool next(int i, Unit& u) const { if (i > 0) return false; u = u0; return true; }
;     __host__ __device__ bool next(int i, Unit& u) const {
;         const long L = (long)i * G + c; if (L >= nwg) return false;
;         int wgid = (int)L; { const int q = nwg / NXCD, r = nwg % NXCD, xcd = wgid % NXCD, off = wgid / NXCD; wgid = (xcd < r ? xcd * (q + 1) : r * (q + 1) + (xcd - r) * q) + off; }
;         const int nig = WGM * nN, gid = wgid / nig, fm = gid * WGM, gsz = (nM - fm) < WGM ? (nM - fm) : WGM;
;         u.pm = fm + ((wgid % nig) % gsz); u.pn = (wgid % nig) / gsz; return true;
;     }
.LBB0_235:
	s_and_b64 s[4:5], s[12:13], exec
	s_movk_i32 s4, 0x88
	s_cselect_b32 s84, 0x80, s4
	s_load_dword s85, s[92:93], 0x0
	s_load_dwordx2 s[8:9], s[56:57], 0x28
	s_load_dwordx2 s[6:7], s[56:57], 0x50
	s_load_dwordx2 s[4:5], s[56:57], 0x70
	s_mul_i32 s60, s84, 28
	v_mov_b32_e32 v15, v168
	s_cmp_lt_i32 s2, s60
	s_cselect_b64 s[10:11], -1, 0
	s_cmp_ge_i32 s2, s60
	v_readfirstlane_b32 s26, v15
	s_cbranch_scc1 .LBB0_237
	s_lshr_b32 s12, s60, 3
	v_readlane_b32 s13, v255, 11
	s_or_b32 s12, s12, s13
	v_readlane_b32 s13, v255, 10
	s_mul_i32 s12, s12, s13
	v_readlane_b32 s13, v255, 8
	s_add_i32 s12, s12, s13
	s_mul_hi_i32 s13, s12, 0x92492493
	s_add_i32 s13, s13, s12
	s_lshr_b32 s16, s13, 31
	s_ashr_i32 s13, s13, 7
	s_add_i32 s13, s13, s16
	s_lshl_b32 s16, s13, 3
	s_mulk_i32 s13, 0xe0
	s_sub_i32 s12, s12, s13
	s_lshr_b32 s20, s12, 3
	s_and_b32 s12, s12, 7
	s_add_i32 s50, s16, s12
	s_bfe_u32 s100, s16, 0x10004
	s_lshl_b32 s100, s100, 4
	s_add_i32 s20, s20, s100
	s_cmp_gt_u32 s20, 27
	s_cselect_b32 s100, 28, 0
	s_sub_i32 s20, s20, s100

;     __device__ __forceinline__ bool next(int i, Unit& u) const { if (i > 0) return false; u = u0; return true; }
;     __host__ __device__ bool next(int i, Unit& u) const {
;         const long L = (long)i * G + c; if (L >= nwg) return false;
;         int wgid = (int)L; { const int q = nwg / NXCD, r = nwg % NXCD, xcd = wgid % NXCD, off = wgid / NXCD; wgid = (xcd < r ? xcd * (q + 1) : r * (q + 1) + (xcd - r) * q) + off; }
;         const int nig = WGM * nN, gid = wgid / nig, fm = gid * WGM, gsz = (nM - fm) < WGM ? (nM - fm) : WGM;
;         u.pm = fm + ((wgid % nig) % gsz); u.pn = (wgid % nig) / gsz; return true;
;     }
; template <class Epi, class Sched, bool ALIGN_EPI = false, bool SP2 = false>
; __device__ __forceinline__ void gemm_phase(PG8_LAS unsigned char* lds, const Gemm g, const Sched& S, const Epi& E) {
;     ...
;         const bool has_next = S.next(ui + 1, nxt);
.LBB0_243:
	s_add_i32 s87, s87, 1
	s_mul_i32 s8, s87, s92
	s_mul_hi_u32 s9, s87, s85
	s_add_i32 s9, s9, s8
	s_mul_i32 s8, s87, s85
	s_add_u32 s26, s8, s2
	s_addc_u32 s27, s9, s22
	v_mov_b64_e32 v[2:3], s[60:61]
	v_cmp_ge_i64_e32 vcc, s[26:27], v[2:3]
	v_cmp_lt_i64_e64 s[8:9], s[26:27], v[2:3]
	s_cbranch_vccnz .LBB0_245
	s_ashr_i32 s21, s26, 31
	s_lshr_b32 s21, s21, 29
	s_add_i32 s21, s26, s21
	s_ashr_i32 s27, s21, 3
	s_and_b32 s21, s21, -8
	s_sub_i32 s21, s26, s21
	s_lshr_b32 s26, s21, 31
	s_or_b32 s26, s93, s26
	s_mul_i32 s21, s26, s21
	s_add_i32 s21, s21, s27
	s_mul_hi_i32 s26, s21, 0x92492493
	s_add_i32 s26, s26, s21
	s_lshr_b32 s27, s26, 31
	s_ashr_i32 s26, s26, 7
	s_add_i32 s26, s26, s27
	s_lshl_b32 s27, s26, 3
	s_mulk_i32 s26, 0xe0
	s_sub_i32 s21, s21, s26
	s_lshr_b32 s42, s21, 3
	s_and_b32 s21, s21, 7
	s_add_i32 s62, s21, s27
	s_bfe_u32 s100, s27, 0x10004
	s_lshl_b32 s100, s100, 4
	s_add_i32 s42, s42, s100
	s_cmp_gt_u32 s42, 27
	s_cselect_b32 s100, 28, 0
	s_sub_i32 s42, s42, s100
